# baseline (speedup 1.0000x reference)
; __device__ __forceinline__ int crow(int r, int hi) { return (r & 3) + 8 * (r >> 2) + 4 * hi; }
; #define SBAR() __builtin_amdgcn_sched_barrier(0)
; #define PV_W8() do { asm volatile("s_waitcnt lgkmcnt(8)" ::: "memory"); SBAR(); } while (0)
; __device__ __forceinline__ void pv256(f32x16* o, int vb, bf16x8 pa0, bf16x8 pa1, bf16x8 pa2, bf16x8 pa3) {
;     s16x4 ra[8], rb[8];
;     asm volatile("s_waitcnt lgkmcnt(0)" ::: "memory");
;     PV_RD8(0, 0, ra);
;     PV_RD8(1, 0, rb); PV_W8(); PV_MMA(o[0], ra);
;     PV_RD8(2, 0, ra); PV_W8(); PV_MMA(o[1], rb);
;     PV_RD8(3, 0, rb); PV_W8(); PV_MMA(o[2], ra);
;     PV_RD8(0, 16384, ra); PV_W8(); PV_MMA(o[3], rb);
;     PV_RD8(1, 16384, rb); PV_W8(); PV_MMA(o[4], ra);
;     PV_RD8(2, 16384, ra); PV_W8(); PV_MMA(o[5], rb);
;     PV_RD8(3, 16384, rb); PV_W8(); PV_MMA(o[6], ra);
;     asm volatile("s_waitcnt lgkmcnt(0)" ::: "memory"); SBAR(); PV_MMA(o[7], rb);
; }
; template <int LDQ, int LDK, int LDV, int LDO>
; __device__ __forceinline__ void attn256_body(const int tid, const bf16_t* __restrict__ Qb, const bf16_t* __restrict__ Kh, const bf16_t* __restrict__ Vh, bf16_t* __restrict__ Ob, int seq, char* lds, LAS unsigned char* ldsl) {
;     ...
;         float ps = 0.f;
; #pragma unroll
;         for (int r = 0; r < 16; ++r) { p0[r] = __builtin_amdgcn_exp2f(fmaf(p0[r], C, mnC)); p1[r] = __builtin_amdgcn_exp2f(fmaf(p1[r], C, mnC)); ps += p0[r] + p1[r]; }
;         { auto rr = __builtin_amdgcn_permlane32_swap(__float_as_uint(ps), __float_as_uint(ps), false, false); ps = __uint_as_float(rr[0]) + __uint_as_float(rr[1]); }
;         l_reg = l_reg * alpha + ps;
;         bf16x8 pa0, pa1, pa2, pa3;
;         PK4(p0, 0, pa0); PK4(p0, 8, pa1); PK4(p1, 0, pa2); PK4(p1, 8, pa3);
;         if (__any(alpha < 1.f)) { if (hi == 0) al_l[r32] = alpha; asm volatile("s_waitcnt lgkmcnt(0)" ::: "memory");
; #pragma unroll
;             for (int r = 0; r < 16; ++r) { const float f = al_l[crow(r, hi)];
; #pragma unroll
;                 for (int d = 0; d < 8; ++d) o[d][r] *= f; } }
;         const int vb = vb0 + b * 32768;
;         pv256(o, vb, pa0, pa1, pa2, pa3);
.Lattn_resc_done_b0:
	v_exp_f32_e32 v130, v130
	v_exp_f32_e32 v131, v131
	v_exp_f32_e32 v132, v132
	v_exp_f32_e32 v133, v133
	v_exp_f32_e32 v134, v134
	v_exp_f32_e32 v135, v135
	v_exp_f32_e32 v136, v136
	v_exp_f32_e32 v137, v137
	v_add_f32_e32 v252, v130, v131
	v_cvt_pk_bf16_f32 v130, v130, v131
	v_add_f32_e32 v208, v132, v133
	v_cvt_pk_bf16_f32 v131, v132, v133
	v_add_f32_e32 v209, v134, v135
	v_cvt_pk_bf16_f32 v132, v134, v135
	v_add_f32_e32 v240, v136, v137
	v_cvt_pk_bf16_f32 v133, v136, v137
	s_nop 0
	v_permlane32_swap_b32_e32 v130, v132
	v_permlane32_swap_b32_e32 v131, v133
	v_add_f32_e32 v252, v252, v208
	v_add_f32_e32 v209, v209, v240
	v_add_f32_e32 v252, v252, v209
	s_waitcnt lgkmcnt(4)
	v_mfma_f32_32x32x16_bf16 v[114:129], v[130:133], v[244:247], v[114:129]
	v_fmamk_f32 v138, v138, 0x3e0293ee, v0
	v_exp_f32_e32 v138, v138
	v_fmamk_f32 v139, v139, 0x3e0293ee, v0
	v_exp_f32_e32 v139, v139
	v_add_f32_e32 v252, v252, v138
	v_fmamk_f32 v140, v140, 0x3e0293ee, v0
	ds_read_b64_tr_b16 v[244:245], v221 offset:0x4400
	ds_read_b64_tr_b16 v[246:247], v221 offset:0x4c00
	v_mfma_f32_32x32x16_bf16 v[98:113], v[130:133], v[248:251], v[98:113]
	v_exp_f32_e32 v140, v140
	v_add_f32_e32 v252, v252, v139
	v_fmamk_f32 v141, v141, 0x3e0293ee, v0
	v_exp_f32_e32 v141, v141
	v_add_f32_e32 v252, v252, v140
	v_fmamk_f32 v142, v142, 0x3e0293ee, v0
	ds_read_b64_tr_b16 v[248:249], v221 offset:0x4600
	ds_read_b64_tr_b16 v[250:251], v221 offset:0x4e00
	v_mfma_f32_32x32x16_bf16 v[82:97], v[130:133], v[224:227], v[82:97]
	v_exp_f32_e32 v142, v142
	v_add_f32_e32 v252, v252, v141
	v_fmamk_f32 v143, v143, 0x3e0293ee, v0
	v_exp_f32_e32 v143, v143
	v_add_f32_e32 v252, v252, v142
	v_fmamk_f32 v144, v144, 0x3e0293ee, v0
	ds_read_b64_tr_b16 v[224:225], v221 offset:0x1000
	ds_read_b64_tr_b16 v[226:227], v221 offset:0x1800
	v_mfma_f32_32x32x16_bf16 v[66:81], v[130:133], v[228:231], v[66:81]
	v_exp_f32_e32 v144, v144
	v_add_f32_e32 v252, v252, v143
	v_fmamk_f32 v145, v145, 0x3e0293ee, v0
	v_exp_f32_e32 v145, v145
	v_add_f32_e32 v252, v252, v144
	v_cvt_pk_bf16_f32 v134, v138, v139
	ds_read_b64_tr_b16 v[228:229], v221 offset:0x1200
	ds_read_b64_tr_b16 v[230:231], v221 offset:0x1a00
	s_waitcnt lgkmcnt(4)
	v_mfma_f32_32x32x16_bf16 v[50:65], v[130:133], v[232:235], v[50:65]
	v_add_f32_e32 v252, v252, v145
	v_cvt_pk_bf16_f32 v135, v140, v141
	v_cvt_pk_bf16_f32 v136, v142, v143
	v_cvt_pk_bf16_f32 v137, v144, v145
	s_nop 0
	v_permlane32_swap_b32_e32 v134, v136
	v_permlane32_swap_b32_e32 v135, v137
	v_fmamk_f32 v146, v146, 0x3e0293ee, v0
	ds_read_b64_tr_b16 v[232:233], v221 offset:0x1400
	ds_read_b64_tr_b16 v[234:235], v221 offset:0x1c00
	v_mfma_f32_32x32x16_bf16 v[34:49], v[130:133], v[236:239], v[34:49]
	v_exp_f32_e32 v146, v146
	v_fmamk_f32 v147, v147, 0x3e0293ee, v0
	v_exp_f32_e32 v147, v147
	v_add_f32_e32 v252, v252, v146
	v_fmamk_f32 v148, v148, 0x3e0293ee, v0
	ds_read_b64_tr_b16 v[236:237], v221 offset:0x1600
	ds_read_b64_tr_b16 v[238:239], v221 offset:0x1e00
	v_mfma_f32_32x32x16_bf16 v[18:33], v[130:133], v[244:247], v[18:33]
	v_exp_f32_e32 v148, v148
	v_add_f32_e32 v252, v252, v147
	v_fmamk_f32 v149, v149, 0x3e0293ee, v0
	v_exp_f32_e32 v149, v149
	v_add_f32_e32 v252, v252, v148
	v_fmamk_f32 v150, v150, 0x3e0293ee, v0
	ds_read_b64_tr_b16 v[244:245], v221 offset:0x5000
	ds_read_b64_tr_b16 v[246:247], v221 offset:0x5800
	v_mfma_f32_32x32x16_bf16 v[2:17], v[130:133], v[248:251], v[2:17]
	v_exp_f32_e32 v150, v150
	v_add_f32_e32 v252, v252, v149
	v_fmamk_f32 v151, v151, 0x3e0293ee, v0
	v_exp_f32_e32 v151, v151
	v_add_f32_e32 v252, v252, v150
	v_fmamk_f32 v152, v152, 0x3e0293ee, v0
	ds_read_b64_tr_b16 v[248:249], v221 offset:0x5200
	ds_read_b64_tr_b16 v[250:251], v221 offset:0x5a00
	s_waitcnt lgkmcnt(4)
	v_mfma_f32_32x32x16_bf16 v[114:129], v[134:137], v[224:227], v[114:129]
	v_exp_f32_e32 v152, v152
	v_add_f32_e32 v252, v252, v151
	v_fmamk_f32 v153, v153, 0x3e0293ee, v0
	v_exp_f32_e32 v153, v153
	v_add_f32_e32 v252, v252, v152
	v_cvt_pk_bf16_f32 v138, v146, v147
	ds_read_b64_tr_b16 v[224:225], v221 offset:0x5400
	ds_read_b64_tr_b16 v[226:227], v221 offset:0x5c00
	v_mfma_f32_32x32x16_bf16 v[98:113], v[134:137], v[228:231], v[98:113]
	v_add_f32_e32 v252, v252, v153
	v_cvt_pk_bf16_f32 v139, v148, v149
	v_cvt_pk_bf16_f32 v140, v150, v151
	v_cvt_pk_bf16_f32 v141, v152, v153
	s_nop 0
	v_permlane32_swap_b32_e32 v138, v140
	v_permlane32_swap_b32_e32 v139, v141
	v_fmamk_f32 v154, v154, 0x3e0293ee, v0
	ds_read_b64_tr_b16 v[228:229], v221 offset:0x5600
	ds_read_b64_tr_b16 v[230:231], v221 offset:0x5e00
	v_mfma_f32_32x32x16_bf16 v[82:97], v[134:137], v[232:235], v[82:97]
	v_exp_f32_e32 v154, v154
	v_fmamk_f32 v155, v155, 0x3e0293ee, v0
	v_exp_f32_e32 v155, v155
	v_add_f32_e32 v252, v252, v154
	v_fmamk_f32 v156, v156, 0x3e0293ee, v0
	ds_read_b64_tr_b16 v[232:233], v221 offset:0x2000
	ds_read_b64_tr_b16 v[234:235], v221 offset:0x2800
	v_mfma_f32_32x32x16_bf16 v[66:81], v[134:137], v[236:239], v[66:81]
	v_exp_f32_e32 v156, v156
	v_add_f32_e32 v252, v252, v155
	v_fmamk_f32 v157, v157, 0x3e0293ee, v0
	v_exp_f32_e32 v157, v157
	v_add_f32_e32 v252, v252, v156
	v_fmamk_f32 v158, v158, 0x3e0293ee, v0
	ds_read_b64_tr_b16 v[236:237], v221 offset:0x2200
	ds_read_b64_tr_b16 v[238:239], v221 offset:0x2a00
	s_waitcnt lgkmcnt(4)
; __device__ __forceinline__ int crow(int r, int hi) { return (r & 3) + 8 * (r >> 2) + 4 * hi; }
; #define SBAR() __builtin_amdgcn_sched_barrier(0)
; #define PV_MMA(OD, R) do { OD = __builtin_amdgcn_mfma_f32_32x32x16_bf16(pa0, PKF(R[0], R[1]), OD, 0, 0, 0); OD = __builtin_amdgcn_mfma_f32_32x32x16_bf16(pa1, PKF(R[2], R[3]), OD, 0, 0, 0); \
;         OD = __builtin_amdgcn_mfma_f32_32x32x16_bf16(pa2, PKF(R[4], R[5]), OD, 0, 0, 0); OD = __builtin_amdgcn_mfma_f32_32x32x16_bf16(pa3, PKF(R[6], R[7]), OD, 0, 0, 0); SBAR(); } while (0)
; __device__ __forceinline__ void pv256(f32x16* o, int vb, bf16x8 pa0, bf16x8 pa1, bf16x8 pa2, bf16x8 pa3) {
;     s16x4 ra[8], rb[8];
;     asm volatile("s_waitcnt lgkmcnt(0)" ::: "memory");
;     PV_RD8(0, 0, ra);
;     PV_RD8(1, 0, rb); PV_W8(); PV_MMA(o[0], ra);
;     PV_RD8(2, 0, ra); PV_W8(); PV_MMA(o[1], rb);
;     PV_RD8(3, 0, rb); PV_W8(); PV_MMA(o[2], ra);
;     PV_RD8(0, 16384, ra); PV_W8(); PV_MMA(o[3], rb);
;     PV_RD8(1, 16384, rb); PV_W8(); PV_MMA(o[4], ra);
;     PV_RD8(2, 16384, ra); PV_W8(); PV_MMA(o[5], rb);
;     PV_RD8(3, 16384, rb); PV_W8(); PV_MMA(o[6], ra);
;     asm volatile("s_waitcnt lgkmcnt(0)" ::: "memory"); SBAR(); PV_MMA(o[7], rb);
; }
; template <int LDQ, int LDK, int LDV, int LDO>
; __device__ __forceinline__ void attn256_body(const int tid, const bf16_t* __restrict__ Qb, const bf16_t* __restrict__ Kh, const bf16_t* __restrict__ Vh, bf16_t* __restrict__ Ob, int seq, char* lds, LAS unsigned char* ldsl) {
;     ...
;         for (int r = 0; r < 16; ++r) { p0[r] = __builtin_amdgcn_exp2f(fmaf(p0[r], C, mnC)); p1[r] = __builtin_amdgcn_exp2f(fmaf(p1[r], C, mnC)); ps += p0[r] + p1[r]; }
;         { auto rr = __builtin_amdgcn_permlane32_swap(__float_as_uint(ps), __float_as_uint(ps), false, false); ps = __uint_as_float(rr[0]) + __uint_as_float(rr[1]); }
;         l_reg = l_reg * alpha + ps;
;         bf16x8 pa0, pa1, pa2, pa3;
;         PK4(p0, 0, pa0); PK4(p0, 8, pa1); PK4(p1, 0, pa2); PK4(p1, 8, pa3);
;         if (__any(alpha < 1.f)) { if (hi == 0) al_l[r32] = alpha; asm volatile("s_waitcnt lgkmcnt(0)" ::: "memory");
; #pragma unroll
;             for (int r = 0; r < 16; ++r) { const float f = al_l[crow(r, hi)];
; #pragma unroll
;                 for (int d = 0; d < 8; ++d) o[d][r] *= f; } }
;         const int vb = vb0 + b * 32768;
;         pv256(o, vb, pa0, pa1, pa2, pa3);
	v_mfma_f32_32x32x16_bf16 v[50:65], v[134:137], v[244:247], v[50:65]
	v_exp_f32_e32 v158, v158
	v_add_f32_e32 v252, v252, v157
	v_fmamk_f32 v159, v159, 0x3e0293ee, v0
	v_exp_f32_e32 v159, v159
	v_add_f32_e32 v252, v252, v158
	v_fmamk_f32 v160, v160, 0x3e0293ee, v0
	ds_read_b64_tr_b16 v[244:245], v221 offset:0x2400
	ds_read_b64_tr_b16 v[246:247], v221 offset:0x2c00
	v_mfma_f32_32x32x16_bf16 v[34:49], v[134:137], v[248:251], v[34:49]
	v_exp_f32_e32 v160, v160
	v_add_f32_e32 v252, v252, v159
	v_fmamk_f32 v161, v161, 0x3e0293ee, v0
	v_exp_f32_e32 v161, v161
	v_add_f32_e32 v252, v252, v160
	v_cvt_pk_bf16_f32 v142, v154, v155
	ds_read_b64_tr_b16 v[248:249], v221 offset:0x2600
	ds_read_b64_tr_b16 v[250:251], v221 offset:0x2e00
	v_mfma_f32_32x32x16_bf16 v[18:33], v[134:137], v[224:227], v[18:33]
	v_add_f32_e32 v252, v252, v161
	v_cvt_pk_bf16_f32 v143, v156, v157
	v_cvt_pk_bf16_f32 v144, v158, v159
	v_cvt_pk_bf16_f32 v145, v160, v161
	s_nop 0
	v_permlane32_swap_b32_e32 v142, v144
	v_permlane32_swap_b32_e32 v143, v145
	v_mov_b32_e32 v240, v252
	ds_read_b64_tr_b16 v[224:225], v221 offset:0x6000
	ds_read_b64_tr_b16 v[226:227], v221 offset:0x6800
	v_mfma_f32_32x32x16_bf16 v[2:17], v[134:137], v[228:231], v[2:17]
	s_nop 1
	v_permlane32_swap_b32_e32 v252, v240
	v_add_f32_e32 v240, v252, v240
	v_fma_f32 v223, v223, v243, v240
	ds_read_b64_tr_b16 v[228:229], v221 offset:0x6200
	ds_read_b64_tr_b16 v[230:231], v221 offset:0x6a00
	s_waitcnt lgkmcnt(4)
	v_mfma_f32_32x32x16_bf16 v[114:129], v[138:141], v[232:235], v[114:129]
	ds_read_b64_tr_b16 v[232:233], v221 offset:0x6400
	ds_read_b64_tr_b16 v[234:235], v221 offset:0x6c00
	v_mfma_f32_32x32x16_bf16 v[98:113], v[138:141], v[236:239], v[98:113]
	ds_read_b64_tr_b16 v[236:237], v221 offset:0x6600
	ds_read_b64_tr_b16 v[238:239], v221 offset:0x6e00
	v_mfma_f32_32x32x16_bf16 v[82:97], v[138:141], v[244:247], v[82:97]
	ds_read_b64_tr_b16 v[244:245], v221 offset:0x3000
	ds_read_b64_tr_b16 v[246:247], v221 offset:0x3800
	v_mfma_f32_32x32x16_bf16 v[66:81], v[138:141], v[248:251], v[66:81]
	ds_read_b64_tr_b16 v[248:249], v221 offset:0x3200
	ds_read_b64_tr_b16 v[250:251], v221 offset:0x3a00
	s_waitcnt lgkmcnt(4)
	v_mfma_f32_32x32x16_bf16 v[50:65], v[138:141], v[224:227], v[50:65]
	ds_read_b64_tr_b16 v[224:225], v221 offset:0x3400
	ds_read_b64_tr_b16 v[226:227], v221 offset:0x3c00
	v_mfma_f32_32x32x16_bf16 v[34:49], v[138:141], v[228:231], v[34:49]
	ds_read_b64_tr_b16 v[228:229], v221 offset:0x3600
	ds_read_b64_tr_b16 v[230:231], v221 offset:0x3e00
	v_mfma_f32_32x32x16_bf16 v[18:33], v[138:141], v[232:235], v[18:33]
	ds_read_b64_tr_b16 v[232:233], v221 offset:0x7000
	ds_read_b64_tr_b16 v[234:235], v221 offset:0x7800
	v_mfma_f32_32x32x16_bf16 v[2:17], v[138:141], v[236:239], v[2:17]
	ds_read_b64_tr_b16 v[236:237], v221 offset:0x7200
	ds_read_b64_tr_b16 v[238:239], v221 offset:0x7a00
	s_waitcnt lgkmcnt(4)
	v_mfma_f32_32x32x16_bf16 v[114:129], v[142:145], v[244:247], v[114:129]
	ds_read_b64_tr_b16 v[244:245], v221 offset:0x7400
	ds_read_b64_tr_b16 v[246:247], v221 offset:0x7c00
	v_mfma_f32_32x32x16_bf16 v[98:113], v[142:145], v[248:251], v[98:113]
	ds_read_b64_tr_b16 v[248:249], v221 offset:0x7600
	ds_read_b64_tr_b16 v[250:251], v221 offset:0x7e00
	v_mfma_f32_32x32x16_bf16 v[82:97], v[142:145], v[224:227], v[82:97]
	v_mfma_f32_32x32x16_bf16 v[66:81], v[142:145], v[228:231], v[66:81]
	s_waitcnt lgkmcnt(0)
	s_waitcnt vmcnt(0)
	s_barrier
	ds_read_b128 v[224:227], v212 offset:16384
	ds_read_b128 v[228:231], v213 offset:16384
	v_mfma_f32_32x32x16_bf16 v[50:65], v[142:145], v[232:235], v[50:65]
	ds_read_b128 v[232:235], v214 offset:16384
	v_mfma_f32_32x32x16_bf16 v[34:49], v[142:145], v[236:239], v[34:49]
	ds_read_b128 v[236:239], v215 offset:16384
	v_mfma_f32_32x32x16_bf16 v[18:33], v[142:145], v[244:247], v[18:33]
	ds_read_b128 v[244:247], v216 offset:16384
	v_mfma_f32_32x32x16_bf16 v[2:17], v[142:145], v[248:251], v[2:17]
	ds_read_b128 v[248:251], v218 offset:16384

; __device__ __forceinline__ int crow(int r, int hi) { return (r & 3) + 8 * (r >> 2) + 4 * hi; }
; #define SBAR() __builtin_amdgcn_sched_barrier(0)
; #define PV_W8() do { asm volatile("s_waitcnt lgkmcnt(8)" ::: "memory"); SBAR(); } while (0)
; __device__ __forceinline__ void pv256(f32x16* o, int vb, bf16x8 pa0, bf16x8 pa1, bf16x8 pa2, bf16x8 pa3) {
;     s16x4 ra[8], rb[8];
;     asm volatile("s_waitcnt lgkmcnt(0)" ::: "memory");
;     PV_RD8(0, 0, ra);
;     PV_RD8(1, 0, rb); PV_W8(); PV_MMA(o[0], ra);
;     PV_RD8(2, 0, ra); PV_W8(); PV_MMA(o[1], rb);
;     PV_RD8(3, 0, rb); PV_W8(); PV_MMA(o[2], ra);
;     PV_RD8(0, 16384, ra); PV_W8(); PV_MMA(o[3], rb);
;     PV_RD8(1, 16384, rb); PV_W8(); PV_MMA(o[4], ra);
;     PV_RD8(2, 16384, ra); PV_W8(); PV_MMA(o[5], rb);
;     PV_RD8(3, 16384, rb); PV_W8(); PV_MMA(o[6], ra);
;     asm volatile("s_waitcnt lgkmcnt(0)" ::: "memory"); SBAR(); PV_MMA(o[7], rb);
; }
; template <int LDQ, int LDK, int LDV, int LDO>
; __device__ __forceinline__ void attn256_body(const int tid, const bf16_t* __restrict__ Qb, const bf16_t* __restrict__ Kh, const bf16_t* __restrict__ Vh, bf16_t* __restrict__ Ob, int seq, char* lds, LAS unsigned char* ldsl) {
;     ...
;         float ps = 0.f;
; #pragma unroll
;         for (int r = 0; r < 16; ++r) { p0[r] = __builtin_amdgcn_exp2f(fmaf(p0[r], C, mnC)); p1[r] = __builtin_amdgcn_exp2f(fmaf(p1[r], C, mnC)); ps += p0[r] + p1[r]; }
;         { auto rr = __builtin_amdgcn_permlane32_swap(__float_as_uint(ps), __float_as_uint(ps), false, false); ps = __uint_as_float(rr[0]) + __uint_as_float(rr[1]); }
;         l_reg = l_reg * alpha + ps;
;         bf16x8 pa0, pa1, pa2, pa3;
;         PK4(p0, 0, pa0); PK4(p0, 8, pa1); PK4(p1, 0, pa2); PK4(p1, 8, pa3);
;         if (__any(alpha < 1.f)) { if (hi == 0) al_l[r32] = alpha; asm volatile("s_waitcnt lgkmcnt(0)" ::: "memory");
; #pragma unroll
;             for (int r = 0; r < 16; ++r) { const float f = al_l[crow(r, hi)];
; #pragma unroll
;                 for (int d = 0; d < 8; ++d) o[d][r] *= f; } }
;         const int vb = vb0 + b * 32768;
;         pv256(o, vb, pa0, pa1, pa2, pa3);
.Lattn_resc_done_b1:
	v_exp_f32_e32 v130, v130
	v_exp_f32_e32 v131, v131
	v_exp_f32_e32 v132, v132
	v_exp_f32_e32 v133, v133
	v_exp_f32_e32 v134, v134
	v_exp_f32_e32 v135, v135
	v_exp_f32_e32 v136, v136
	v_exp_f32_e32 v137, v137
	v_add_f32_e32 v252, v130, v131
	v_cvt_pk_bf16_f32 v130, v130, v131
	v_add_f32_e32 v208, v132, v133
	v_cvt_pk_bf16_f32 v131, v132, v133
	v_add_f32_e32 v209, v134, v135
	v_cvt_pk_bf16_f32 v132, v134, v135
	v_add_f32_e32 v240, v136, v137
	v_cvt_pk_bf16_f32 v133, v136, v137
	s_nop 0
	v_permlane32_swap_b32_e32 v130, v132
	v_permlane32_swap_b32_e32 v131, v133
	v_add_f32_e32 v252, v252, v208
	v_add_f32_e32 v209, v209, v240
	v_add_f32_e32 v252, v252, v209
	s_waitcnt lgkmcnt(4)
	v_mfma_f32_32x32x16_bf16 v[114:129], v[130:133], v[244:247], v[114:129]
	v_fmamk_f32 v138, v138, 0x3e0293ee, v0
	v_exp_f32_e32 v138, v138
	v_fmamk_f32 v139, v139, 0x3e0293ee, v0
	v_exp_f32_e32 v139, v139
	v_add_f32_e32 v252, v252, v138
	v_fmamk_f32 v140, v140, 0x3e0293ee, v0
	ds_read_b64_tr_b16 v[244:245], v221 offset:0xc400
	ds_read_b64_tr_b16 v[246:247], v221 offset:0xcc00
	v_mfma_f32_32x32x16_bf16 v[98:113], v[130:133], v[248:251], v[98:113]
	v_exp_f32_e32 v140, v140
	v_add_f32_e32 v252, v252, v139
	v_fmamk_f32 v141, v141, 0x3e0293ee, v0
	v_exp_f32_e32 v141, v141
	v_add_f32_e32 v252, v252, v140
	v_fmamk_f32 v142, v142, 0x3e0293ee, v0
	ds_read_b64_tr_b16 v[248:249], v221 offset:0xc600
	ds_read_b64_tr_b16 v[250:251], v221 offset:0xce00
	v_mfma_f32_32x32x16_bf16 v[82:97], v[130:133], v[224:227], v[82:97]
	v_exp_f32_e32 v142, v142
	v_add_f32_e32 v252, v252, v141
	v_fmamk_f32 v143, v143, 0x3e0293ee, v0
	v_exp_f32_e32 v143, v143
	v_add_f32_e32 v252, v252, v142
	v_fmamk_f32 v144, v144, 0x3e0293ee, v0
	ds_read_b64_tr_b16 v[224:225], v221 offset:0x9000
	ds_read_b64_tr_b16 v[226:227], v221 offset:0x9800
	v_mfma_f32_32x32x16_bf16 v[66:81], v[130:133], v[228:231], v[66:81]
	v_exp_f32_e32 v144, v144
	v_add_f32_e32 v252, v252, v143
	v_fmamk_f32 v145, v145, 0x3e0293ee, v0
	v_exp_f32_e32 v145, v145
	v_add_f32_e32 v252, v252, v144
	v_cvt_pk_bf16_f32 v134, v138, v139
	ds_read_b64_tr_b16 v[228:229], v221 offset:0x9200
	ds_read_b64_tr_b16 v[230:231], v221 offset:0x9a00
	s_waitcnt lgkmcnt(4)
	v_mfma_f32_32x32x16_bf16 v[50:65], v[130:133], v[232:235], v[50:65]
	v_add_f32_e32 v252, v252, v145
	v_cvt_pk_bf16_f32 v135, v140, v141
	v_cvt_pk_bf16_f32 v136, v142, v143
	v_cvt_pk_bf16_f32 v137, v144, v145
	s_nop 0
	v_permlane32_swap_b32_e32 v134, v136
	v_permlane32_swap_b32_e32 v135, v137
	v_fmamk_f32 v146, v146, 0x3e0293ee, v0
	ds_read_b64_tr_b16 v[232:233], v221 offset:0x9400
	ds_read_b64_tr_b16 v[234:235], v221 offset:0x9c00
	v_mfma_f32_32x32x16_bf16 v[34:49], v[130:133], v[236:239], v[34:49]
	v_exp_f32_e32 v146, v146
	v_fmamk_f32 v147, v147, 0x3e0293ee, v0
	v_exp_f32_e32 v147, v147
	v_add_f32_e32 v252, v252, v146
	v_fmamk_f32 v148, v148, 0x3e0293ee, v0
	ds_read_b64_tr_b16 v[236:237], v221 offset:0x9600
	ds_read_b64_tr_b16 v[238:239], v221 offset:0x9e00
	v_mfma_f32_32x32x16_bf16 v[18:33], v[130:133], v[244:247], v[18:33]
	v_exp_f32_e32 v148, v148
	v_add_f32_e32 v252, v252, v147
	v_fmamk_f32 v149, v149, 0x3e0293ee, v0
	v_exp_f32_e32 v149, v149
	v_add_f32_e32 v252, v252, v148
	v_fmamk_f32 v150, v150, 0x3e0293ee, v0
	ds_read_b64_tr_b16 v[244:245], v221 offset:0xd000
	ds_read_b64_tr_b16 v[246:247], v221 offset:0xd800
	v_mfma_f32_32x32x16_bf16 v[2:17], v[130:133], v[248:251], v[2:17]
	v_exp_f32_e32 v150, v150
	v_add_f32_e32 v252, v252, v149
	v_fmamk_f32 v151, v151, 0x3e0293ee, v0
	v_exp_f32_e32 v151, v151
	v_add_f32_e32 v252, v252, v150
	v_fmamk_f32 v152, v152, 0x3e0293ee, v0
	ds_read_b64_tr_b16 v[248:249], v221 offset:0xd200
	ds_read_b64_tr_b16 v[250:251], v221 offset:0xda00
	s_waitcnt lgkmcnt(4)
	v_mfma_f32_32x32x16_bf16 v[114:129], v[134:137], v[224:227], v[114:129]
	v_exp_f32_e32 v152, v152
	v_add_f32_e32 v252, v252, v151
	v_fmamk_f32 v153, v153, 0x3e0293ee, v0
	v_exp_f32_e32 v153, v153
	v_add_f32_e32 v252, v252, v152
	v_cvt_pk_bf16_f32 v138, v146, v147
	ds_read_b64_tr_b16 v[224:225], v221 offset:0xd400
	ds_read_b64_tr_b16 v[226:227], v221 offset:0xdc00
	v_mfma_f32_32x32x16_bf16 v[98:113], v[134:137], v[228:231], v[98:113]
	v_add_f32_e32 v252, v252, v153
	v_cvt_pk_bf16_f32 v139, v148, v149
	v_cvt_pk_bf16_f32 v140, v150, v151
	v_cvt_pk_bf16_f32 v141, v152, v153
	s_nop 0
	v_permlane32_swap_b32_e32 v138, v140
	v_permlane32_swap_b32_e32 v139, v141
	v_fmamk_f32 v154, v154, 0x3e0293ee, v0
	ds_read_b64_tr_b16 v[228:229], v221 offset:0xd600
	ds_read_b64_tr_b16 v[230:231], v221 offset:0xde00
	v_mfma_f32_32x32x16_bf16 v[82:97], v[134:137], v[232:235], v[82:97]
	v_exp_f32_e32 v154, v154
	v_fmamk_f32 v155, v155, 0x3e0293ee, v0
	v_exp_f32_e32 v155, v155
	v_add_f32_e32 v252, v252, v154
	v_fmamk_f32 v156, v156, 0x3e0293ee, v0
	ds_read_b64_tr_b16 v[232:233], v221 offset:0xa000
	ds_read_b64_tr_b16 v[234:235], v221 offset:0xa800
	v_mfma_f32_32x32x16_bf16 v[66:81], v[134:137], v[236:239], v[66:81]
	v_exp_f32_e32 v156, v156
	v_add_f32_e32 v252, v252, v155
	v_fmamk_f32 v157, v157, 0x3e0293ee, v0
	v_exp_f32_e32 v157, v157
	v_add_f32_e32 v252, v252, v156
	v_fmamk_f32 v158, v158, 0x3e0293ee, v0
	ds_read_b64_tr_b16 v[236:237], v221 offset:0xa200
	ds_read_b64_tr_b16 v[238:239], v221 offset:0xaa00
	s_waitcnt lgkmcnt(4)
; __device__ __forceinline__ int crow(int r, int hi) { return (r & 3) + 8 * (r >> 2) + 4 * hi; }
; #define SBAR() __builtin_amdgcn_sched_barrier(0)
; #define PV_W8() do { asm volatile("s_waitcnt lgkmcnt(8)" ::: "memory"); SBAR(); } while (0)
; __device__ __forceinline__ void pv256(f32x16* o, int vb, bf16x8 pa0, bf16x8 pa1, bf16x8 pa2, bf16x8 pa3) {
;     s16x4 ra[8], rb[8];
;     asm volatile("s_waitcnt lgkmcnt(0)" ::: "memory");
;     PV_RD8(0, 0, ra);
;     PV_RD8(1, 0, rb); PV_W8(); PV_MMA(o[0], ra);
;     PV_RD8(2, 0, ra); PV_W8(); PV_MMA(o[1], rb);
;     PV_RD8(3, 0, rb); PV_W8(); PV_MMA(o[2], ra);
;     PV_RD8(0, 16384, ra); PV_W8(); PV_MMA(o[3], rb);
;     PV_RD8(1, 16384, rb); PV_W8(); PV_MMA(o[4], ra);
;     PV_RD8(2, 16384, ra); PV_W8(); PV_MMA(o[5], rb);
;     PV_RD8(3, 16384, rb); PV_W8(); PV_MMA(o[6], ra);
;     asm volatile("s_waitcnt lgkmcnt(0)" ::: "memory"); SBAR(); PV_MMA(o[7], rb);
; }
; template <int LDQ, int LDK, int LDV, int LDO>
; __device__ __forceinline__ void attn256_body(const int tid, const bf16_t* __restrict__ Qb, const bf16_t* __restrict__ Kh, const bf16_t* __restrict__ Vh, bf16_t* __restrict__ Ob, int seq, char* lds, LAS unsigned char* ldsl) {
;     ...
;     for (int j = 0; j < NT; ++j) {
;         const int b = j & 1;
;         asm volatile("s_waitcnt vmcnt(0)" ::: "memory"); __builtin_amdgcn_s_barrier(); asm volatile("" ::: "memory");
;     ...
;         for (int r = 0; r < 16; ++r) { p0[r] = __builtin_amdgcn_exp2f(fmaf(p0[r], C, mnC)); p1[r] = __builtin_amdgcn_exp2f(fmaf(p1[r], C, mnC)); ps += p0[r] + p1[r]; }
;         { auto rr = __builtin_amdgcn_permlane32_swap(__float_as_uint(ps), __float_as_uint(ps), false, false); ps = __uint_as_float(rr[0]) + __uint_as_float(rr[1]); }
;         l_reg = l_reg * alpha + ps;
;         bf16x8 pa0, pa1, pa2, pa3;
;         PK4(p0, 0, pa0); PK4(p0, 8, pa1); PK4(p1, 0, pa2); PK4(p1, 8, pa3);
;         if (__any(alpha < 1.f)) { if (hi == 0) al_l[r32] = alpha; asm volatile("s_waitcnt lgkmcnt(0)" ::: "memory");
; #pragma unroll
;             for (int r = 0; r < 16; ++r) { const float f = al_l[crow(r, hi)];
; #pragma unroll
;                 for (int d = 0; d < 8; ++d) o[d][r] *= f; } }
;         const int vb = vb0 + b * 32768;
;         pv256(o, vb, pa0, pa1, pa2, pa3);
	v_mfma_f32_32x32x16_bf16 v[50:65], v[134:137], v[244:247], v[50:65]
	v_exp_f32_e32 v158, v158
	v_add_f32_e32 v252, v252, v157
	v_fmamk_f32 v159, v159, 0x3e0293ee, v0
	v_exp_f32_e32 v159, v159
	v_add_f32_e32 v252, v252, v158
	v_fmamk_f32 v160, v160, 0x3e0293ee, v0
	ds_read_b64_tr_b16 v[244:245], v221 offset:0xa400
	ds_read_b64_tr_b16 v[246:247], v221 offset:0xac00
	v_mfma_f32_32x32x16_bf16 v[34:49], v[134:137], v[248:251], v[34:49]
	v_exp_f32_e32 v160, v160
	v_add_f32_e32 v252, v252, v159
	v_fmamk_f32 v161, v161, 0x3e0293ee, v0
	v_exp_f32_e32 v161, v161
	v_add_f32_e32 v252, v252, v160
	v_cvt_pk_bf16_f32 v142, v154, v155
	ds_read_b64_tr_b16 v[248:249], v221 offset:0xa600
	ds_read_b64_tr_b16 v[250:251], v221 offset:0xae00
	v_mfma_f32_32x32x16_bf16 v[18:33], v[134:137], v[224:227], v[18:33]
	v_add_f32_e32 v252, v252, v161
	v_cvt_pk_bf16_f32 v143, v156, v157
	v_cvt_pk_bf16_f32 v144, v158, v159
	v_cvt_pk_bf16_f32 v145, v160, v161
	s_nop 0
	v_permlane32_swap_b32_e32 v142, v144
	v_permlane32_swap_b32_e32 v143, v145
	v_mov_b32_e32 v240, v252
	ds_read_b64_tr_b16 v[224:225], v221 offset:0xe000
	ds_read_b64_tr_b16 v[226:227], v221 offset:0xe800
	v_mfma_f32_32x32x16_bf16 v[2:17], v[134:137], v[228:231], v[2:17]
	s_nop 1
	v_permlane32_swap_b32_e32 v252, v240
	v_add_f32_e32 v240, v252, v240
	v_fma_f32 v223, v223, v243, v240
	ds_read_b64_tr_b16 v[228:229], v221 offset:0xe200
	ds_read_b64_tr_b16 v[230:231], v221 offset:0xea00
	s_waitcnt lgkmcnt(4)
	v_mfma_f32_32x32x16_bf16 v[114:129], v[138:141], v[232:235], v[114:129]
	ds_read_b64_tr_b16 v[232:233], v221 offset:0xe400
	ds_read_b64_tr_b16 v[234:235], v221 offset:0xec00
	v_mfma_f32_32x32x16_bf16 v[98:113], v[138:141], v[236:239], v[98:113]
	ds_read_b64_tr_b16 v[236:237], v221 offset:0xe600
	ds_read_b64_tr_b16 v[238:239], v221 offset:0xee00
	v_mfma_f32_32x32x16_bf16 v[82:97], v[138:141], v[244:247], v[82:97]
	ds_read_b64_tr_b16 v[244:245], v221 offset:0xb000
	ds_read_b64_tr_b16 v[246:247], v221 offset:0xb800
	v_mfma_f32_32x32x16_bf16 v[66:81], v[138:141], v[248:251], v[66:81]
	ds_read_b64_tr_b16 v[248:249], v221 offset:0xb200
	ds_read_b64_tr_b16 v[250:251], v221 offset:0xba00
	s_waitcnt lgkmcnt(4)
	v_mfma_f32_32x32x16_bf16 v[50:65], v[138:141], v[224:227], v[50:65]
	ds_read_b64_tr_b16 v[224:225], v221 offset:0xb400
	ds_read_b64_tr_b16 v[226:227], v221 offset:0xbc00
	v_mfma_f32_32x32x16_bf16 v[34:49], v[138:141], v[228:231], v[34:49]
	ds_read_b64_tr_b16 v[228:229], v221 offset:0xb600
	ds_read_b64_tr_b16 v[230:231], v221 offset:0xbe00
	v_mfma_f32_32x32x16_bf16 v[18:33], v[138:141], v[232:235], v[18:33]
	ds_read_b64_tr_b16 v[232:233], v221 offset:0xf000
	ds_read_b64_tr_b16 v[234:235], v221 offset:0xf800
	v_mfma_f32_32x32x16_bf16 v[2:17], v[138:141], v[236:239], v[2:17]
	ds_read_b64_tr_b16 v[236:237], v221 offset:0xf200
	ds_read_b64_tr_b16 v[238:239], v221 offset:0xfa00
	s_waitcnt lgkmcnt(4)
	v_mfma_f32_32x32x16_bf16 v[114:129], v[142:145], v[244:247], v[114:129]
	ds_read_b64_tr_b16 v[244:245], v221 offset:0xf400
	ds_read_b64_tr_b16 v[246:247], v221 offset:0xfc00
	v_mfma_f32_32x32x16_bf16 v[98:113], v[142:145], v[248:251], v[98:113]
	ds_read_b64_tr_b16 v[248:249], v221 offset:0xf600
	ds_read_b64_tr_b16 v[250:251], v221 offset:0xfe00
	v_mfma_f32_32x32x16_bf16 v[82:97], v[142:145], v[224:227], v[82:97]
	v_mfma_f32_32x32x16_bf16 v[66:81], v[142:145], v[228:231], v[66:81]
	s_waitcnt lgkmcnt(0)
	s_waitcnt vmcnt(0)
	s_barrier
	ds_read_b128 v[224:227], v212
	ds_read_b128 v[228:231], v213
	v_mfma_f32_32x32x16_bf16 v[50:65], v[142:145], v[232:235], v[50:65]
	ds_read_b128 v[232:235], v214
	v_mfma_f32_32x32x16_bf16 v[34:49], v[142:145], v[236:239], v[34:49]
	ds_read_b128 v[236:239], v215
	v_mfma_f32_32x32x16_bf16 v[18:33], v[142:145], v[244:247], v[18:33]
	ds_read_b128 v[244:247], v216
	v_mfma_f32_32x32x16_bf16 v[2:17], v[142:145], v[248:251], v[2:17]
	ds_read_b128 v[248:251], v218
	s_cmp_eq_u32 s23, 64
	s_cbranch_scc0 .LBB0_134
	s_waitcnt lgkmcnt(0)
	v_mov_b32_e32 v146, v223
	s_branch .LBB0_143
